# retention epilogue: xor-16 reduction step via v_permlane16_swap instead of ds_bpermute
# baseline (speedup 1.0000x reference)
; #define LAS __attribute__((address_space(3)))
; DI int crow(int r, int hi) { return (r & 3) + 8 * (r >> 2) + 4 * hi; }
; #define MFMA32(a, b, c) __builtin_amdgcn_mfma_f32_32x32x16_bf16((a), (b), (c), 0, 0, 0)
; DI void phase_ret_out(const Params& p, const Grp& G, int layer, LAS unsigned char* lds, int tid, int wave, int lane, bool dry) {
;     ...
;         for (int dir = 0; dir < 2; ++dir) {
;             const LAS bf16_t* S = Sl + (hh * 2 + dir) * 4096; f32x16 t[2]; t[0] = f32x16{}; t[1] = f32x16{};
; #pragma unroll
;             for (int ks = 0; ks < 4; ++ks) {
; #pragma unroll
;                 for (int cb = 0; cb < 2; ++cb) { const LAS bf16_t* sp = S + (16 * ks + 8 * hi) * 64 + 32 * cb + l31;
;                     u32x4 w; w.x = (unsigned)sp[0] | ((unsigned)sp[64] << 16); w.y = (unsigned)sp[128] | ((unsigned)sp[192] << 16); w.z = (unsigned)sp[256] | ((unsigned)sp[320] << 16); w.w = (unsigned)sp[384] | ((unsigned)sp[448] << 16);
;                     t[cb] = MFMA32(qf[ks], __builtin_bit_cast(bf16x8, w), t[cb]); }
;                 asm volatile("" ::: "memory"); }
; #pragma unroll
;             for (int r = 0; r < 16; ++r) { const int nrow = 32 * qg + crow(r, hi); const float sc = dir == 0 ? __builtin_amdgcn_exp2f(lgf * (float)(nrow + 1)) : __builtin_amdgcn_exp2f(lgb * (float)(128 - nrow));
;                 o[0][r] += t[0][r] * sc; o[1][r] += t[1][r] * sc; }
.LBB0_424:
	v_cndmask_b32_e64 v16, 0, 1, s[30:31]
	v_add_u32_e32 v227, s0, v151
	v_cmp_ne_u32_e32 vcc, 1, v16
	s_movk_i32 s0, 0x2000
	s_and_b64 vcc, exec, vcc
	ds_read_u16 v228, v227
	ds_read_u16 v232, v227 offset:128
	ds_read_u16 v229, v227 offset:256
	ds_read_u16 v233, v227 offset:384
	ds_read_u16 v230, v227 offset:512
	ds_read_u16 v234, v227 offset:640
	ds_read_u16 v231, v227 offset:768
	ds_read_u16 v235, v227 offset:896
	ds_read_u16 v236, v227 offset:64
	ds_read_u16 v240, v227 offset:192
	ds_read_u16 v237, v227 offset:320
	ds_read_u16 v241, v227 offset:448
	s_waitcnt lgkmcnt(4)
	v_lshl_or_b32 v228, v232, 16, v228
	v_lshl_or_b32 v229, v233, 16, v229
	v_lshl_or_b32 v230, v234, 16, v230
	v_lshl_or_b32 v231, v235, 16, v231
	ds_read_u16 v238, v227 offset:576
	ds_read_u16 v248, v227 offset:704
	ds_read_u16 v239, v227 offset:832
	ds_read_u16 v249, v227 offset:960
	v_mfma_f32_32x32x16_bf16 v[16:31], v[112:115], v[228:231], 0
	ds_read_u16 v228, v227 offset:2048
	ds_read_u16 v232, v227 offset:2176
	ds_read_u16 v229, v227 offset:2304
	ds_read_u16 v233, v227 offset:2432
	s_waitcnt lgkmcnt(4)
	v_lshl_or_b32 v236, v240, 16, v236
	v_lshl_or_b32 v237, v241, 16, v237
	v_lshl_or_b32 v238, v248, 16, v238
	v_lshl_or_b32 v239, v249, 16, v239
	ds_read_u16 v230, v227 offset:2560
	ds_read_u16 v234, v227 offset:2688
	ds_read_u16 v231, v227 offset:2816
	ds_read_u16 v235, v227 offset:2944
	v_mfma_f32_32x32x16_bf16 v[32:47], v[112:115], v[236:239], 0
	ds_read_u16 v236, v227 offset:2112
	ds_read_u16 v240, v227 offset:2240
	ds_read_u16 v237, v227 offset:2368
	ds_read_u16 v241, v227 offset:2496
	s_waitcnt lgkmcnt(4)
	v_lshl_or_b32 v228, v232, 16, v228
	v_lshl_or_b32 v229, v233, 16, v229
	v_lshl_or_b32 v230, v234, 16, v230
	v_lshl_or_b32 v231, v235, 16, v231
	ds_read_u16 v238, v227 offset:2624
	ds_read_u16 v248, v227 offset:2752
	ds_read_u16 v239, v227 offset:2880
	ds_read_u16 v249, v227 offset:3008
	v_mfma_f32_32x32x16_bf16 v[16:31], v[116:119], v[228:231], v[16:31]
	ds_read_u16 v228, v227 offset:4096
	ds_read_u16 v232, v227 offset:4224
	ds_read_u16 v229, v227 offset:4352
	ds_read_u16 v233, v227 offset:4480
	s_waitcnt lgkmcnt(4)
	v_lshl_or_b32 v236, v240, 16, v236
	v_lshl_or_b32 v237, v241, 16, v237
	v_lshl_or_b32 v238, v248, 16, v238
	v_lshl_or_b32 v239, v249, 16, v239
	ds_read_u16 v230, v227 offset:4608
	ds_read_u16 v234, v227 offset:4736
	ds_read_u16 v231, v227 offset:4864
	ds_read_u16 v235, v227 offset:4992
	v_mfma_f32_32x32x16_bf16 v[32:47], v[116:119], v[236:239], v[32:47]
	ds_read_u16 v236, v227 offset:4160
	ds_read_u16 v240, v227 offset:4288
	ds_read_u16 v237, v227 offset:4416
	ds_read_u16 v241, v227 offset:4544
	s_waitcnt lgkmcnt(4)
	v_lshl_or_b32 v228, v232, 16, v228
	v_lshl_or_b32 v229, v233, 16, v229
	v_lshl_or_b32 v230, v234, 16, v230
	v_lshl_or_b32 v231, v235, 16, v231
	ds_read_u16 v238, v227 offset:4672
	ds_read_u16 v248, v227 offset:4800
	ds_read_u16 v239, v227 offset:4928
	ds_read_u16 v249, v227 offset:5056
	v_mfma_f32_32x32x16_bf16 v[16:31], v[120:123], v[228:231], v[16:31]
	ds_read_u16 v228, v227 offset:6144
	ds_read_u16 v232, v227 offset:6272
	ds_read_u16 v229, v227 offset:6400
	ds_read_u16 v233, v227 offset:6528
	s_waitcnt lgkmcnt(4)
	v_lshl_or_b32 v236, v240, 16, v236
	v_lshl_or_b32 v237, v241, 16, v237
	v_lshl_or_b32 v238, v248, 16, v238
	v_lshl_or_b32 v239, v249, 16, v239
	ds_read_u16 v230, v227 offset:6656
	ds_read_u16 v234, v227 offset:6784
	ds_read_u16 v231, v227 offset:6912
	ds_read_u16 v235, v227 offset:7040
	v_mfma_f32_32x32x16_bf16 v[32:47], v[120:123], v[236:239], v[32:47]
	ds_read_u16 v236, v227 offset:6208
	ds_read_u16 v240, v227 offset:6336
	ds_read_u16 v237, v227 offset:6464
	ds_read_u16 v241, v227 offset:6592
	s_waitcnt lgkmcnt(4)
	v_lshl_or_b32 v228, v232, 16, v228
	v_lshl_or_b32 v229, v233, 16, v229
	v_lshl_or_b32 v230, v234, 16, v230
	v_lshl_or_b32 v231, v235, 16, v231
	ds_read_u16 v238, v227 offset:6720
	ds_read_u16 v248, v227 offset:6848
	ds_read_u16 v239, v227 offset:6976
	ds_read_u16 v249, v227 offset:7104
	v_mfma_f32_32x32x16_bf16 v[16:31], v[124:127], v[228:231], v[16:31]
	s_waitcnt lgkmcnt(0)
	v_lshl_or_b32 v236, v240, 16, v236
	v_lshl_or_b32 v237, v241, 16, v237
	v_lshl_or_b32 v238, v248, 16, v238
	v_lshl_or_b32 v239, v249, 16, v239
	s_nop 1
	v_mfma_f32_32x32x16_bf16 v[32:47], v[124:127], v[236:239], v[32:47]
	s_nop 4
	v_mov_b32_e32 v230, v16
	v_cndmask_b32_e64 v16, v190, v191, s[30:31]
	v_cndmask_b32_e64 v228, v188, v189, s[30:31]
	s_nop 8
	v_mov_b32_e32 v231, v32
	v_mov_b32_e32 v32, v17
	v_pk_fma_f32 v[148:149], v[16:17], v[32:33], v[148:149] op_sel_hi:[0,1,1]
	v_cndmask_b32_e64 v16, v192, v196, s[30:31]
	v_mov_b32_e32 v32, v18
	v_mov_b32_e32 v33, v34
	v_pk_fma_f32 v[2:3], v[16:17], v[32:33], v[2:3] op_sel_hi:[0,1,1]
	v_cndmask_b32_e64 v16, v197, v198, s[30:31]
	v_mov_b32_e32 v34, v19
	v_pk_fma_f32 v[146:147], v[16:17], v[34:35], v[146:147] op_sel_hi:[0,1,1]
	v_cndmask_b32_e64 v16, v199, v200, s[30:31]
	v_mov_b32_e32 v18, v20
	v_mov_b32_e32 v19, v36
	v_pk_fma_f32 v[4:5], v[16:17], v[18:19], v[4:5] op_sel_hi:[0,1,1]
	v_cndmask_b32_e64 v16, v201, v202, s[30:31]
	v_mov_b32_e32 v36, v21
	v_pk_fma_f32 v[144:145], v[16:17], v[36:37], v[144:145] op_sel_hi:[0,1,1]
	v_cndmask_b32_e64 v16, v203, v204, s[30:31]
	v_mov_b32_e32 v18, v22
	v_mov_b32_e32 v19, v38
	v_pk_fma_f32 v[6:7], v[16:17], v[18:19], v[6:7] op_sel_hi:[0,1,1]
	v_cndmask_b32_e64 v16, v205, v206, s[30:31]
	v_mov_b32_e32 v38, v23
	v_pk_fma_f32 v[142:143], v[16:17], v[38:39], v[142:143] op_sel_hi:[0,1,1]
	v_cndmask_b32_e64 v16, v207, v208, s[30:31]
	v_mov_b32_e32 v18, v24
	v_mov_b32_e32 v19, v40
	v_pk_fma_f32 v[8:9], v[16:17], v[18:19], v[8:9] op_sel_hi:[0,1,1]
	v_cndmask_b32_e64 v16, v209, v210, s[30:31]
	v_mov_b32_e32 v40, v25
	v_pk_fma_f32 v[140:141], v[16:17], v[40:41], v[140:141] op_sel_hi:[0,1,1]
	v_cndmask_b32_e64 v16, v211, v216, s[30:31]
	v_mov_b32_e32 v18, v26
	v_mov_b32_e32 v19, v42
	v_pk_fma_f32 v[10:11], v[16:17], v[18:19], v[10:11] op_sel_hi:[0,1,1]
	v_cndmask_b32_e64 v16, v217, v218, s[30:31]
	v_mov_b32_e32 v42, v27
	v_pk_fma_f32 v[138:139], v[16:17], v[42:43], v[138:139] op_sel_hi:[0,1,1]
	v_cndmask_b32_e64 v16, v219, v220, s[30:31]
	v_mov_b32_e32 v18, v28
	v_mov_b32_e32 v19, v44
	v_pk_fma_f32 v[12:13], v[16:17], v[18:19], v[12:13] op_sel_hi:[0,1,1]
	v_cndmask_b32_e64 v16, v221, v222, s[30:31]
	v_mov_b32_e32 v44, v29
	v_pk_fma_f32 v[136:137], v[16:17], v[44:45], v[136:137] op_sel_hi:[0,1,1]
	v_cndmask_b32_e64 v16, v223, v224, s[30:31]
	v_mov_b32_e32 v18, v30
	v_mov_b32_e32 v19, v46
	v_pk_fma_f32 v[14:15], v[16:17], v[18:19], v[14:15] op_sel_hi:[0,1,1]
	v_cndmask_b32_e64 v16, v225, v226, s[30:31]
	v_mov_b32_e32 v46, v31
	v_pk_fma_f32 v[0:1], v[228:229], v[230:231], v[0:1] op_sel_hi:[0,1,1]
	v_pk_fma_f32 v[134:135], v[16:17], v[46:47], v[134:135] op_sel_hi:[0,1,1]
	s_mov_b64 s[30:31], 0
	s_cbranch_vccz .LBB0_424
; #define LAS __attribute__((address_space(3)))
; DI int crow(int r, int hi) { return (r & 3) + 8 * (r >> 2) + 4 * hi; }
; DI void phase_ret_out(const Params& p, const Grp& G, int layer, LAS unsigned char* lds, int tid, int wave, int lane, bool dry) {
;     ...
;         const float g0 = p.gn[layer * 64 + l31], g1 = p.gn[layer * 64 + 32 + l31];
;         __syncthreads();
;         LAS float* stg = (LAS float*)(lds + wave * 8192);
; #pragma unroll
;         for (int r = 0; r < 16; ++r) {
;             float ss = o[0][r] * o[0][r] + o[1][r] * o[1][r]; ss = half_sum32(ss); const float ri = rsqrtf(ss * (1.0f / 64.0f) + EPSN);
;             LAS float* sp = stg + crow(r, hi) * 64 + l31; sp[0] = o[0][r] * ri * g0; sp[32] = o[1][r] * ri * g1;
;         }
	global_load_dword v19, v[132:133], off
	global_load_dword v18, v[132:133], off offset:128
	v_pk_mul_f32 v[16:17], v[0:1], v[0:1]
	v_pk_mul_f32 v[20:21], v[148:149], v[148:149]
	v_mov_b32_e32 v23, v16
	v_mov_b32_e32 v22, v20
	v_mov_b32_e32 v16, v21
	v_pk_add_f32 v[16:17], v[22:23], v[16:17]
	s_mov_b32 s0, 0x358637bd
	s_waitcnt lgkmcnt(0)
	s_barrier
	s_nop 1
	v_add_f32_dpp v16, v16, v16 quad_perm:[1,0,3,2] row_mask:0xf bank_mask:0xf
	v_add_f32_dpp v17, v17, v17 quad_perm:[1,0,3,2] row_mask:0xf bank_mask:0xf
	s_waitcnt lgkmcnt(0)
	s_nop 1
	v_add_f32_dpp v16, v16, v16 quad_perm:[2,3,0,1] row_mask:0xf bank_mask:0xf
	v_add_f32_dpp v17, v17, v17 quad_perm:[2,3,0,1] row_mask:0xf bank_mask:0xf
	s_waitcnt lgkmcnt(0)
	s_nop 1
	v_add_f32_dpp v16, v16, v16 row_half_mirror row_mask:0xf bank_mask:0xf
	v_add_f32_dpp v17, v17, v17 row_half_mirror row_mask:0xf bank_mask:0xf
	s_waitcnt lgkmcnt(0)
	s_nop 1
	v_add_f32_dpp v16, v16, v16 row_ror:8 row_mask:0xf bank_mask:0xf
	v_add_f32_dpp v17, v17, v17 row_ror:8 row_mask:0xf bank_mask:0xf
	v_mov_b32_e32 v20, v16
	v_mov_b32_e32 v21, v17
	s_nop 1
	v_permlane16_swap_b32_e32 v16, v20
	v_permlane16_swap_b32_e32 v17, v21
	s_waitcnt lgkmcnt(0)
	v_pk_add_f32 v[20:21], v[16:17], v[20:21]
	v_mov_b64_e32 v[16:17], s[0:1]
	s_mov_b32 s0, 0x3c800000
	v_pk_fma_f32 v[20:21], v[20:21], s[0:1], v[16:17] op_sel_hi:[1,0,0]
	s_nop 0
	v_mul_f32_e32 v22, 0x4b800000, v21
	v_cmp_gt_f32_e64 s[38:39], s90, v21
	v_cmp_gt_f32_e32 vcc, s90, v20
	s_nop 0
	v_cndmask_b32_e64 v21, v21, v22, s[38:39]
	v_rsq_f32_e32 v21, v21
	s_nop 0
	v_mul_f32_e32 v22, 0x45800000, v21
	v_cndmask_b32_e64 v21, v21, v22, s[38:39]
	v_mul_f32_e32 v0, v0, v21
	v_mul_f32_e32 v1, v1, v21
	s_waitcnt vmcnt(1)
	v_mul_f32_e32 v0, v19, v0
	s_waitcnt vmcnt(0)
	v_mul_f32_e32 v1, v18, v1
	ds_write2_b32 v152, v0, v1 offset1:32
	v_mul_f32_e32 v0, 0x4b800000, v20
	v_cndmask_b32_e32 v0, v20, v0, vcc
	v_rsq_f32_e32 v0, v0
	v_pk_mul_f32 v[20:21], v[146:147], v[146:147]
	v_mul_f32_e32 v1, 0x45800000, v0
	v_cndmask_b32_e32 v0, v0, v1, vcc
	v_mul_f32_e32 v1, v148, v0
	v_mul_f32_e32 v0, v149, v0
	v_mul_f32_e32 v1, v19, v1
	v_mul_f32_e32 v0, v18, v0
	ds_write2_b32 v152, v1, v0 offset0:64 offset1:96
	v_pk_mul_f32 v[0:1], v[2:3], v[2:3]
	v_mov_b32_e32 v22, v20
	v_mov_b32_e32 v23, v0
	v_mov_b32_e32 v0, v21
	v_pk_add_f32 v[0:1], v[22:23], v[0:1]
	s_waitcnt lgkmcnt(0)
	s_nop 1
	v_add_f32_dpp v0, v0, v0 quad_perm:[1,0,3,2] row_mask:0xf bank_mask:0xf
	v_add_f32_dpp v1, v1, v1 quad_perm:[1,0,3,2] row_mask:0xf bank_mask:0xf
	s_waitcnt lgkmcnt(0)
	s_nop 1
	v_add_f32_dpp v0, v0, v0 quad_perm:[2,3,0,1] row_mask:0xf bank_mask:0xf
	v_add_f32_dpp v1, v1, v1 quad_perm:[2,3,0,1] row_mask:0xf bank_mask:0xf
	s_waitcnt lgkmcnt(0)
	s_nop 1
	v_add_f32_dpp v0, v0, v0 row_half_mirror row_mask:0xf bank_mask:0xf
	v_add_f32_dpp v1, v1, v1 row_half_mirror row_mask:0xf bank_mask:0xf
	s_waitcnt lgkmcnt(0)
	s_nop 1
	v_add_f32_dpp v0, v0, v0 row_ror:8 row_mask:0xf bank_mask:0xf
	v_add_f32_dpp v1, v1, v1 row_ror:8 row_mask:0xf bank_mask:0xf
	v_mov_b32_e32 v20, v0
	v_mov_b32_e32 v21, v1
	s_nop 1
	v_permlane16_swap_b32_e32 v0, v20
	v_permlane16_swap_b32_e32 v1, v21
	s_waitcnt lgkmcnt(0)
	v_pk_add_f32 v[0:1], v[0:1], v[20:21]
	s_nop 0
	v_pk_fma_f32 v[0:1], v[0:1], s[0:1], v[16:17] op_sel_hi:[1,0,0]
	s_nop 0
	v_mul_f32_e32 v20, 0x4b800000, v1
	v_cmp_gt_f32_e64 s[38:39], s90, v1
	v_cmp_gt_f32_e32 vcc, s90, v0
	s_nop 0
	v_cndmask_b32_e64 v1, v1, v20, s[38:39]
	v_rsq_f32_e32 v1, v1
	s_nop 0
	v_mul_f32_e32 v20, 0x45800000, v1
	v_cndmask_b32_e64 v1, v1, v20, s[38:39]
	v_mul_f32_e32 v2, v2, v1
	v_mul_f32_e32 v1, v3, v1
	v_mul_f32_e32 v2, v19, v2
	v_mul_f32_e32 v1, v18, v1
	ds_write2_b32 v152, v2, v1 offset0:128 offset1:160
	v_mul_f32_e32 v1, 0x4b800000, v0
	v_cndmask_b32_e32 v0, v0, v1, vcc
	v_rsq_f32_e32 v0, v0
	v_pk_mul_f32 v[2:3], v[144:145], v[144:145]
	v_mul_f32_e32 v1, 0x45800000, v0
	v_cndmask_b32_e32 v0, v0, v1, vcc
	v_mul_f32_e32 v1, v146, v0
	v_mul_f32_e32 v0, v147, v0
	v_mul_f32_e32 v1, v19, v1
	v_mul_f32_e32 v0, v18, v0
	ds_write2_b32 v152, v1, v0 offset0:192 offset1:224
	v_pk_mul_f32 v[0:1], v[4:5], v[4:5]
	v_mov_b32_e32 v20, v2
	v_mov_b32_e32 v21, v0
	v_mov_b32_e32 v0, v3
	v_pk_add_f32 v[0:1], v[20:21], v[0:1]
	v_add_u32_e32 v20, 0x800, v152
	s_waitcnt lgkmcnt(0)
	s_nop 1
	v_add_f32_dpp v0, v0, v0 quad_perm:[1,0,3,2] row_mask:0xf bank_mask:0xf
	v_add_f32_dpp v1, v1, v1 quad_perm:[1,0,3,2] row_mask:0xf bank_mask:0xf
	s_waitcnt lgkmcnt(0)
	s_nop 1
	v_add_f32_dpp v0, v0, v0 quad_perm:[2,3,0,1] row_mask:0xf bank_mask:0xf
	v_add_f32_dpp v1, v1, v1 quad_perm:[2,3,0,1] row_mask:0xf bank_mask:0xf
	s_waitcnt lgkmcnt(0)
	s_nop 1
	v_add_f32_dpp v0, v0, v0 row_half_mirror row_mask:0xf bank_mask:0xf
	v_add_f32_dpp v1, v1, v1 row_half_mirror row_mask:0xf bank_mask:0xf
	s_waitcnt lgkmcnt(0)
	s_nop 1
	v_add_f32_dpp v0, v0, v0 row_ror:8 row_mask:0xf bank_mask:0xf
	v_add_f32_dpp v1, v1, v1 row_ror:8 row_mask:0xf bank_mask:0xf
	v_mov_b32_e32 v2, v0
	v_mov_b32_e32 v3, v1
	s_nop 1
	v_permlane16_swap_b32_e32 v0, v2
	v_permlane16_swap_b32_e32 v1, v3
	s_waitcnt lgkmcnt(0)
	v_pk_add_f32 v[0:1], v[0:1], v[2:3]
	s_nop 0
	v_pk_fma_f32 v[0:1], v[0:1], s[0:1], v[16:17] op_sel_hi:[1,0,0]
	s_nop 0
	v_mul_f32_e32 v2, 0x4b800000, v1
	v_cmp_gt_f32_e64 s[38:39], s90, v1
	v_cmp_gt_f32_e32 vcc, s90, v0
	s_nop 0
	v_cndmask_b32_e64 v1, v1, v2, s[38:39]
	v_rsq_f32_e32 v1, v1
	s_nop 0
	v_mul_f32_e32 v2, 0x45800000, v1
	v_cndmask_b32_e64 v1, v1, v2, s[38:39]
	v_mul_f32_e32 v2, v4, v1
	v_mul_f32_e32 v1, v5, v1
	v_mul_f32_e32 v2, v19, v2
	v_mul_f32_e32 v1, v18, v1
	ds_write2_b32 v20, v2, v1 offset1:32
	v_mul_f32_e32 v1, 0x4b800000, v0
	v_cndmask_b32_e32 v0, v0, v1, vcc
	v_rsq_f32_e32 v0, v0
	v_pk_mul_f32 v[2:3], v[142:143], v[142:143]
	v_mul_f32_e32 v1, 0x45800000, v0
	v_cndmask_b32_e32 v0, v0, v1, vcc
	v_mul_f32_e32 v1, v144, v0
	v_mul_f32_e32 v0, v145, v0
	v_mul_f32_e32 v1, v19, v1
	v_mul_f32_e32 v0, v18, v0
	ds_write2_b32 v20, v1, v0 offset0:64 offset1:96
	v_pk_mul_f32 v[0:1], v[6:7], v[6:7]
	v_mov_b32_e32 v4, v2
	v_mov_b32_e32 v5, v0
	v_mov_b32_e32 v0, v3
	v_pk_add_f32 v[0:1], v[4:5], v[0:1]
	s_waitcnt lgkmcnt(0)
; #define LAS __attribute__((address_space(3)))
; DI int crow(int r, int hi) { return (r & 3) + 8 * (r >> 2) + 4 * hi; }
; DI void phase_ret_out(const Params& p, const Grp& G, int layer, LAS unsigned char* lds, int tid, int wave, int lane, bool dry) {
;     ...
; #pragma unroll
;         for (int r = 0; r < 16; ++r) {
;             float ss = o[0][r] * o[0][r] + o[1][r] * o[1][r]; ss = half_sum32(ss); const float ri = rsqrtf(ss * (1.0f / 64.0f) + EPSN);
;             LAS float* sp = stg + crow(r, hi) * 64 + l31; sp[0] = o[0][r] * ri * g0; sp[32] = o[1][r] * ri * g1;
;         }
	s_nop 1
	v_add_f32_dpp v0, v0, v0 quad_perm:[1,0,3,2] row_mask:0xf bank_mask:0xf
	v_add_f32_dpp v1, v1, v1 quad_perm:[1,0,3,2] row_mask:0xf bank_mask:0xf
	s_waitcnt lgkmcnt(0)
	s_nop 1
	v_add_f32_dpp v0, v0, v0 quad_perm:[2,3,0,1] row_mask:0xf bank_mask:0xf
	v_add_f32_dpp v1, v1, v1 quad_perm:[2,3,0,1] row_mask:0xf bank_mask:0xf
	s_waitcnt lgkmcnt(0)
	s_nop 1
	v_add_f32_dpp v0, v0, v0 row_half_mirror row_mask:0xf bank_mask:0xf
	v_add_f32_dpp v1, v1, v1 row_half_mirror row_mask:0xf bank_mask:0xf
	s_waitcnt lgkmcnt(0)
	s_nop 1
	v_add_f32_dpp v0, v0, v0 row_ror:8 row_mask:0xf bank_mask:0xf
	v_add_f32_dpp v1, v1, v1 row_ror:8 row_mask:0xf bank_mask:0xf
	v_mov_b32_e32 v2, v0
	v_mov_b32_e32 v3, v1
	s_nop 1
	v_permlane16_swap_b32_e32 v0, v2
	v_permlane16_swap_b32_e32 v1, v3
	s_waitcnt lgkmcnt(0)
	v_pk_add_f32 v[0:1], v[0:1], v[2:3]
	s_nop 0
	v_pk_fma_f32 v[0:1], v[0:1], s[0:1], v[16:17] op_sel_hi:[1,0,0]
	s_nop 0
	v_mul_f32_e32 v2, 0x4b800000, v1
	v_cmp_gt_f32_e64 s[38:39], s90, v1
	v_cmp_gt_f32_e32 vcc, s90, v0
	s_nop 0
	v_cndmask_b32_e64 v1, v1, v2, s[38:39]
	v_rsq_f32_e32 v1, v1
	s_nop 0
	v_mul_f32_e32 v2, 0x45800000, v1
	v_cndmask_b32_e64 v1, v1, v2, s[38:39]
	v_mul_f32_e32 v2, v6, v1
	v_mul_f32_e32 v1, v7, v1
	v_mul_f32_e32 v2, v19, v2
	v_mul_f32_e32 v1, v18, v1
	ds_write2_b32 v20, v2, v1 offset0:128 offset1:160
	v_mul_f32_e32 v1, 0x4b800000, v0
	v_cndmask_b32_e32 v0, v0, v1, vcc
	v_rsq_f32_e32 v0, v0
	v_pk_mul_f32 v[2:3], v[140:141], v[140:141]
	v_add_u32_e32 v6, 0x1000, v152
	v_mov_b32_e32 v4, v2
	v_mul_f32_e32 v1, 0x45800000, v0
	v_cndmask_b32_e32 v0, v0, v1, vcc
	v_mul_f32_e32 v1, v142, v0
	v_mul_f32_e32 v0, v143, v0
	v_mul_f32_e32 v1, v19, v1
	v_mul_f32_e32 v0, v18, v0
	ds_write2_b32 v20, v1, v0 offset0:192 offset1:224
	v_pk_mul_f32 v[0:1], v[8:9], v[8:9]
	s_nop 0
	v_mov_b32_e32 v5, v0
	v_mov_b32_e32 v0, v3
	v_pk_add_f32 v[0:1], v[4:5], v[0:1]
	s_waitcnt lgkmcnt(0)
	s_nop 1
	v_add_f32_dpp v0, v0, v0 quad_perm:[1,0,3,2] row_mask:0xf bank_mask:0xf
	v_add_f32_dpp v1, v1, v1 quad_perm:[1,0,3,2] row_mask:0xf bank_mask:0xf
	s_waitcnt lgkmcnt(0)
	s_nop 1
	v_add_f32_dpp v0, v0, v0 quad_perm:[2,3,0,1] row_mask:0xf bank_mask:0xf
	v_add_f32_dpp v1, v1, v1 quad_perm:[2,3,0,1] row_mask:0xf bank_mask:0xf
	s_waitcnt lgkmcnt(0)
	s_nop 1
	v_add_f32_dpp v0, v0, v0 row_half_mirror row_mask:0xf bank_mask:0xf
	v_add_f32_dpp v1, v1, v1 row_half_mirror row_mask:0xf bank_mask:0xf
	s_waitcnt lgkmcnt(0)
	s_nop 1
	v_add_f32_dpp v0, v0, v0 row_ror:8 row_mask:0xf bank_mask:0xf
	v_add_f32_dpp v1, v1, v1 row_ror:8 row_mask:0xf bank_mask:0xf
	v_mov_b32_e32 v2, v0
	v_mov_b32_e32 v3, v1
	s_nop 1
	v_permlane16_swap_b32_e32 v0, v2
	v_permlane16_swap_b32_e32 v1, v3
	s_waitcnt lgkmcnt(0)
	v_pk_add_f32 v[0:1], v[0:1], v[2:3]
	s_nop 0
	v_pk_fma_f32 v[0:1], v[0:1], s[0:1], v[16:17] op_sel_hi:[1,0,0]
	s_nop 0
	v_mul_f32_e32 v2, 0x4b800000, v1
	v_cmp_gt_f32_e64 s[38:39], s90, v1
	v_cmp_gt_f32_e32 vcc, s90, v0
	s_nop 0
	v_cndmask_b32_e64 v1, v1, v2, s[38:39]
	v_rsq_f32_e32 v1, v1
	s_nop 0
	v_mul_f32_e32 v2, 0x45800000, v1
	v_cndmask_b32_e64 v1, v1, v2, s[38:39]
	v_mul_f32_e32 v2, v8, v1
	v_mul_f32_e32 v1, v9, v1
	v_mul_f32_e32 v2, v19, v2
	v_mul_f32_e32 v1, v18, v1
	ds_write2_b32 v6, v2, v1 offset1:32
	v_mul_f32_e32 v1, 0x4b800000, v0
	v_cndmask_b32_e32 v0, v0, v1, vcc
	v_rsq_f32_e32 v0, v0
	v_pk_mul_f32 v[2:3], v[138:139], v[138:139]
	v_mul_f32_e32 v1, 0x45800000, v0
	v_cndmask_b32_e32 v0, v0, v1, vcc
	v_mul_f32_e32 v1, v140, v0
	v_mul_f32_e32 v0, v141, v0
	v_mul_f32_e32 v1, v19, v1
	v_mul_f32_e32 v0, v18, v0
	ds_write2_b32 v6, v1, v0 offset0:64 offset1:96
	v_pk_mul_f32 v[0:1], v[10:11], v[10:11]
	v_mov_b32_e32 v4, v2
	v_mov_b32_e32 v5, v0
	v_mov_b32_e32 v0, v3
	v_pk_add_f32 v[0:1], v[4:5], v[0:1]
	s_waitcnt lgkmcnt(0)
	s_nop 1
	v_add_f32_dpp v0, v0, v0 quad_perm:[1,0,3,2] row_mask:0xf bank_mask:0xf
	v_add_f32_dpp v1, v1, v1 quad_perm:[1,0,3,2] row_mask:0xf bank_mask:0xf
	s_waitcnt lgkmcnt(0)
	s_nop 1
	v_add_f32_dpp v0, v0, v0 quad_perm:[2,3,0,1] row_mask:0xf bank_mask:0xf
	v_add_f32_dpp v1, v1, v1 quad_perm:[2,3,0,1] row_mask:0xf bank_mask:0xf
	s_waitcnt lgkmcnt(0)
	s_nop 1
	v_add_f32_dpp v0, v0, v0 row_half_mirror row_mask:0xf bank_mask:0xf
	v_add_f32_dpp v1, v1, v1 row_half_mirror row_mask:0xf bank_mask:0xf
	s_waitcnt lgkmcnt(0)
	s_nop 1
	v_add_f32_dpp v0, v0, v0 row_ror:8 row_mask:0xf bank_mask:0xf
	v_add_f32_dpp v1, v1, v1 row_ror:8 row_mask:0xf bank_mask:0xf
	v_mov_b32_e32 v2, v0
	v_mov_b32_e32 v3, v1
	s_nop 1
	v_permlane16_swap_b32_e32 v0, v2
	v_permlane16_swap_b32_e32 v1, v3
	s_waitcnt lgkmcnt(0)
	v_pk_add_f32 v[0:1], v[0:1], v[2:3]
	s_nop 0
	v_pk_fma_f32 v[0:1], v[0:1], s[0:1], v[16:17] op_sel_hi:[1,0,0]
	s_nop 0
	v_mul_f32_e32 v2, 0x4b800000, v1
	v_cmp_gt_f32_e64 s[38:39], s90, v1
	v_cmp_gt_f32_e32 vcc, s90, v0
	s_nop 0
	v_cndmask_b32_e64 v1, v1, v2, s[38:39]
	v_rsq_f32_e32 v1, v1
	s_nop 0
	v_mul_f32_e32 v2, 0x45800000, v1
	v_cndmask_b32_e64 v1, v1, v2, s[38:39]
	v_mul_f32_e32 v2, v10, v1
	v_mul_f32_e32 v1, v11, v1
	v_mul_f32_e32 v2, v19, v2
	v_mul_f32_e32 v1, v18, v1
	ds_write2_b32 v6, v2, v1 offset0:128 offset1:160
	v_mul_f32_e32 v1, 0x4b800000, v0
	v_cndmask_b32_e32 v0, v0, v1, vcc
	v_rsq_f32_e32 v0, v0
	v_pk_mul_f32 v[2:3], v[136:137], v[136:137]
	v_mul_f32_e32 v1, 0x45800000, v0
	v_cndmask_b32_e32 v0, v0, v1, vcc
	v_mul_f32_e32 v1, v138, v0
	v_mul_f32_e32 v0, v139, v0
	v_mul_f32_e32 v1, v19, v1
	v_mul_f32_e32 v0, v18, v0
	ds_write2_b32 v6, v1, v0 offset0:192 offset1:224
	v_pk_mul_f32 v[0:1], v[12:13], v[12:13]
	v_mov_b32_e32 v4, v2
	v_mov_b32_e32 v5, v0
	v_mov_b32_e32 v0, v3
	v_pk_add_f32 v[0:1], v[4:5], v[0:1]
	v_add_u32_e32 v6, 0x1800, v152
	s_waitcnt lgkmcnt(0)
; #define LAS __attribute__((address_space(3)))
; DI unsigned pk2(float lo, float hi) { typedef float f2 __attribute__((ext_vector_type(2))); typedef __bf16 b2 __attribute__((ext_vector_type(2))); f2 v = {lo, hi}; b2 b = __builtin_convertvector(v, b2); return __builtin_bit_cast(unsigned, b); }
; DI float bf_lo(unsigned w) { return __uint_as_float(w << 16); }
; DI float bf_hi(unsigned w) { return __uint_as_float(w & 0xffff0000u); }
; DI int crow(int r, int hi) { return (r & 3) + 8 * (r >> 2) + 4 * hi; }
; DI void phase_ret_out(const Params& p, const Grp& G, int layer, LAS unsigned char* lds, int tid, int wave, int lane, bool dry) {
;     ...
; #pragma unroll
;         for (int r = 0; r < 16; ++r) {
;             float ss = o[0][r] * o[0][r] + o[1][r] * o[1][r]; ss = half_sum32(ss); const float ri = rsqrtf(ss * (1.0f / 64.0f) + EPSN);
;             LAS float* sp = stg + crow(r, hi) * 64 + l31; sp[0] = o[0][r] * ri * g0; sp[32] = o[1][r] * ri * g1;
;         }
;         asm volatile("s_waitcnt lgkmcnt(0)" ::: "memory");
;         { int lv = lane; asm volatile("" : "+v"(lv));
;           bf16_t* ob = (dry ? (bf16_t*)(p.ws + OFF_DUMMY) : mix + row0 * MIXW) + (size_t)(32 * qg) * MIXW + 512 + head * 64; const bf16_t* gb = rest + (row0 + 32 * qg) * RESTW + R_RG + head * 64;
; #pragma unroll
;           for (int i = 0; i < 4; ++i) { const int q = lv + 64 * i, row = q >> 3, ch = q & 7;
;             const f32x4 a0 = *(const LAS f32x4*)(stg + row * 64 + ch * 8), a1 = *(const LAS f32x4*)(stg + row * 64 + ch * 8 + 4);
;             const u32x4 gw = gwv[i];
;             float gv[8] = {bf_lo(gw.x), bf_hi(gw.x), bf_lo(gw.y), bf_hi(gw.y), bf_lo(gw.z), bf_hi(gw.z), bf_lo(gw.w), bf_hi(gw.w)}; float ov[8];
; #pragma unroll
;             for (int e = 0; e < 8; ++e) ov[e] = (e < 4 ? a0[e & 3] : a1[e & 3]) * (gv[e] * __builtin_amdgcn_rcpf(1.f + __expf(-gv[e])));
;             u32x4 w; w.x = pk2(ov[0], ov[1]); w.y = pk2(ov[2], ov[3]); w.z = pk2(ov[4], ov[5]); w.w = pk2(ov[6], ov[7]);
;             *(u32x4*)(ob + (size_t)row * MIXW + ch * 8) = w; } }
	s_nop 1
	v_add_f32_dpp v0, v0, v0 quad_perm:[1,0,3,2] row_mask:0xf bank_mask:0xf
	v_add_f32_dpp v1, v1, v1 quad_perm:[1,0,3,2] row_mask:0xf bank_mask:0xf
	s_waitcnt lgkmcnt(0)
	s_nop 1
	v_add_f32_dpp v0, v0, v0 quad_perm:[2,3,0,1] row_mask:0xf bank_mask:0xf
	v_add_f32_dpp v1, v1, v1 quad_perm:[2,3,0,1] row_mask:0xf bank_mask:0xf
	s_waitcnt lgkmcnt(0)
	s_nop 1
	v_add_f32_dpp v0, v0, v0 row_half_mirror row_mask:0xf bank_mask:0xf
	v_add_f32_dpp v1, v1, v1 row_half_mirror row_mask:0xf bank_mask:0xf
	s_waitcnt lgkmcnt(0)
	s_nop 1
	v_add_f32_dpp v0, v0, v0 row_ror:8 row_mask:0xf bank_mask:0xf
	v_add_f32_dpp v1, v1, v1 row_ror:8 row_mask:0xf bank_mask:0xf
	v_mov_b32_e32 v2, v0
	v_mov_b32_e32 v3, v1
	s_nop 1
	v_permlane16_swap_b32_e32 v0, v2
	v_permlane16_swap_b32_e32 v1, v3
	s_waitcnt lgkmcnt(0)
	v_pk_add_f32 v[0:1], v[0:1], v[2:3]
	s_nop 0
	v_pk_fma_f32 v[0:1], v[0:1], s[0:1], v[16:17] op_sel_hi:[1,0,0]
	s_nop 0
	v_mul_f32_e32 v2, 0x4b800000, v1
	v_cmp_gt_f32_e64 s[38:39], s90, v1
	v_cmp_gt_f32_e32 vcc, s90, v0
	s_nop 0
	v_cndmask_b32_e64 v1, v1, v2, s[38:39]
	v_rsq_f32_e32 v1, v1
	s_nop 0
	v_mul_f32_e32 v2, 0x45800000, v1
	v_cndmask_b32_e64 v1, v1, v2, s[38:39]
	v_mul_f32_e32 v2, v12, v1
	v_mul_f32_e32 v1, v13, v1
	v_mul_f32_e32 v2, v19, v2
	v_mul_f32_e32 v1, v18, v1
	ds_write2_b32 v6, v2, v1 offset1:32
	v_mul_f32_e32 v1, 0x4b800000, v0
	v_cndmask_b32_e32 v0, v0, v1, vcc
	v_rsq_f32_e32 v0, v0
	v_pk_mul_f32 v[2:3], v[134:135], v[134:135]
	v_mul_f32_e32 v1, 0x45800000, v0
	v_cndmask_b32_e32 v0, v0, v1, vcc
	v_mul_f32_e32 v1, v136, v0
	v_mul_f32_e32 v0, v137, v0
	v_mul_f32_e32 v1, v19, v1
	v_mul_f32_e32 v0, v18, v0
	ds_write2_b32 v6, v1, v0 offset0:64 offset1:96
	v_pk_mul_f32 v[0:1], v[14:15], v[14:15]
	v_mov_b32_e32 v4, v2
	v_mov_b32_e32 v5, v0
	v_mov_b32_e32 v0, v3
	v_pk_add_f32 v[0:1], v[4:5], v[0:1]
	s_waitcnt lgkmcnt(0)
	s_nop 1
	v_add_f32_dpp v0, v0, v0 quad_perm:[1,0,3,2] row_mask:0xf bank_mask:0xf
	v_add_f32_dpp v1, v1, v1 quad_perm:[1,0,3,2] row_mask:0xf bank_mask:0xf
	s_waitcnt lgkmcnt(0)
	s_nop 1
	v_add_f32_dpp v0, v0, v0 quad_perm:[2,3,0,1] row_mask:0xf bank_mask:0xf
	v_add_f32_dpp v1, v1, v1 quad_perm:[2,3,0,1] row_mask:0xf bank_mask:0xf
	s_waitcnt lgkmcnt(0)
	s_nop 1
	v_add_f32_dpp v0, v0, v0 row_half_mirror row_mask:0xf bank_mask:0xf
	v_add_f32_dpp v1, v1, v1 row_half_mirror row_mask:0xf bank_mask:0xf
	s_waitcnt lgkmcnt(0)
	s_nop 1
	v_add_f32_dpp v0, v0, v0 row_ror:8 row_mask:0xf bank_mask:0xf
	v_add_f32_dpp v1, v1, v1 row_ror:8 row_mask:0xf bank_mask:0xf
	v_mov_b32_e32 v2, v0
	v_mov_b32_e32 v3, v1
	s_nop 1
	v_permlane16_swap_b32_e32 v0, v2
	v_permlane16_swap_b32_e32 v1, v3
	s_waitcnt lgkmcnt(0)
	v_pk_add_f32 v[0:1], v[0:1], v[2:3]
	s_nop 0
	v_pk_fma_f32 v[0:1], v[0:1], s[0:1], v[16:17] op_sel_hi:[1,0,0]
	s_lshl_b64 s[0:1], s[42:43], 11
	v_mul_f32_e32 v2, 0x4b800000, v1
	v_cmp_gt_f32_e64 s[38:39], s90, v1
	v_cmp_gt_f32_e32 vcc, s90, v0
	s_add_u32 s0, s45, s0
	v_cndmask_b32_e64 v1, v1, v2, s[38:39]
	v_rsq_f32_e32 v1, v1
	s_addc_u32 s1, s52, s1
	s_lshl_b32 s4, s4, 1
	s_add_u32 s0, s0, s4
	v_mul_f32_e32 v2, 0x45800000, v1
	v_cndmask_b32_e64 v1, v1, v2, s[38:39]
	v_mul_f32_e32 v2, v14, v1
	v_mul_f32_e32 v1, v15, v1
	v_mul_f32_e32 v2, v19, v2
	v_mul_f32_e32 v1, v18, v1
	ds_write2_b32 v6, v2, v1 offset0:128 offset1:160
	v_mul_f32_e32 v1, 0x4b800000, v0
	v_cndmask_b32_e32 v0, v0, v1, vcc
	v_lshlrev_b32_e32 v14, 16, v108
	v_rsq_f32_e32 v0, v0
	v_mul_f32_e32 v13, 0xbfb8aa3b, v14
	v_exp_f32_e32 v13, v13
	v_and_b32_e32 v15, 0xffff0000, v108
	v_mul_f32_e32 v1, 0x45800000, v0
	v_cndmask_b32_e32 v0, v0, v1, vcc
	v_add_f32_e32 v13, 1.0, v13
	v_mul_f32_e32 v1, v134, v0
	v_mul_f32_e32 v0, v135, v0
	v_rcp_f32_e32 v16, v13
	v_mul_f32_e32 v13, 0xbfb8aa3b, v15
	v_mul_f32_e32 v1, v19, v1
	v_mul_f32_e32 v0, v18, v0
	v_exp_f32_e32 v13, v13
	ds_write2_b32 v6, v1, v0 offset0:192 offset1:224
	v_mov_b32_e32 v2, v129
	s_waitcnt lgkmcnt(0)
	v_add_f32_e32 v13, 1.0, v13
	v_lshlrev_b32_e32 v0, 3, v2
	v_and_b32_e32 v0, 56, v0
	v_lshl_add_u32 v3, v0, 2, s60
	v_ashrrev_i32_e32 v12, 3, v2
	v_lshl_add_u32 v8, v12, 8, v3
	v_rcp_f32_e32 v17, v13
	ds_read_b128 v[4:7], v8
	ds_read_b128 v[8:11], v8 offset:16
	s_addc_u32 s1, s1, 0
	v_lshlrev_b32_e32 v192, 1, v0
	v_pk_mul_f32 v[14:15], v[16:17], v[14:15]
	v_lshl_add_u64 v[0:1], s[0:1], 0, v[192:193]
	s_waitcnt lgkmcnt(1)
	v_pk_mul_f32 v[4:5], v[14:15], v[4:5]
	v_lshlrev_b32_e32 v14, 16, v109
	v_mul_f32_e32 v13, 0xbfb8aa3b, v14
	v_exp_f32_e32 v13, v13
	v_and_b32_e32 v15, 0xffff0000, v109
	v_cvt_pk_bf16_f32 v4, v4, v5
	s_and_b64 vcc, exec, s[40:41]
	v_add_f32_e32 v13, 1.0, v13
	v_rcp_f32_e32 v16, v13
	v_mul_f32_e32 v13, 0xbfb8aa3b, v15
	v_exp_f32_e32 v13, v13
	s_nop 0
	v_add_f32_e32 v13, 1.0, v13
	v_rcp_f32_e32 v17, v13
	s_nop 0
	v_pk_mul_f32 v[14:15], v[16:17], v[14:15]
	s_nop 0
	v_pk_mul_f32 v[6:7], v[14:15], v[6:7]
	v_lshlrev_b32_e32 v14, 16, v110
	v_mul_f32_e32 v13, 0xbfb8aa3b, v14
	v_exp_f32_e32 v13, v13
	v_and_b32_e32 v15, 0xffff0000, v110
	v_cvt_pk_bf16_f32 v5, v6, v7
	v_add_f32_e32 v13, 1.0, v13
	v_rcp_f32_e32 v16, v13
	v_mul_f32_e32 v13, 0xbfb8aa3b, v15
	v_exp_f32_e32 v13, v13
	s_nop 0
	v_add_f32_e32 v13, 1.0, v13
	v_rcp_f32_e32 v17, v13
	s_nop 0
	v_pk_mul_f32 v[14:15], v[16:17], v[14:15]
	s_waitcnt lgkmcnt(0)
; #define LAS __attribute__((address_space(3)))
; DI unsigned pk2(float lo, float hi) { typedef float f2 __attribute__((ext_vector_type(2))); typedef __bf16 b2 __attribute__((ext_vector_type(2))); f2 v = {lo, hi}; b2 b = __builtin_convertvector(v, b2); return __builtin_bit_cast(unsigned, b); }
; DI float bf_lo(unsigned w) { return __uint_as_float(w << 16); }
; DI float bf_hi(unsigned w) { return __uint_as_float(w & 0xffff0000u); }
; DI void phase_ret_out(const Params& p, const Grp& G, int layer, LAS unsigned char* lds, int tid, int wave, int lane, bool dry) {
;     ...
;         { int lv = lane; asm volatile("" : "+v"(lv));
;           bf16_t* ob = (dry ? (bf16_t*)(p.ws + OFF_DUMMY) : mix + row0 * MIXW) + (size_t)(32 * qg) * MIXW + 512 + head * 64; const bf16_t* gb = rest + (row0 + 32 * qg) * RESTW + R_RG + head * 64;
; #pragma unroll
;           for (int i = 0; i < 4; ++i) { const int q = lv + 64 * i, row = q >> 3, ch = q & 7;
;             const f32x4 a0 = *(const LAS f32x4*)(stg + row * 64 + ch * 8), a1 = *(const LAS f32x4*)(stg + row * 64 + ch * 8 + 4);
;             const u32x4 gw = gwv[i];
;             float gv[8] = {bf_lo(gw.x), bf_hi(gw.x), bf_lo(gw.y), bf_hi(gw.y), bf_lo(gw.z), bf_hi(gw.z), bf_lo(gw.w), bf_hi(gw.w)}; float ov[8];
; #pragma unroll
;             for (int e = 0; e < 8; ++e) ov[e] = (e < 4 ? a0[e & 3] : a1[e & 3]) * (gv[e] * __builtin_amdgcn_rcpf(1.f + __expf(-gv[e])));
;             u32x4 w; w.x = pk2(ov[0], ov[1]); w.y = pk2(ov[2], ov[3]); w.z = pk2(ov[4], ov[5]); w.w = pk2(ov[6], ov[7]);
;             *(u32x4*)(ob + (size_t)row * MIXW + ch * 8) = w; } }
	v_pk_mul_f32 v[8:9], v[14:15], v[8:9]
	v_lshlrev_b32_e32 v14, 16, v111
	v_mul_f32_e32 v13, 0xbfb8aa3b, v14
	v_exp_f32_e32 v13, v13
	v_and_b32_e32 v15, 0xffff0000, v111
	v_cvt_pk_bf16_f32 v6, v8, v9
	v_add_f32_e32 v13, 1.0, v13
	v_rcp_f32_e32 v16, v13
	v_mul_f32_e32 v13, 0xbfb8aa3b, v15
	v_exp_f32_e32 v13, v13
	s_nop 0
	v_add_f32_e32 v13, 1.0, v13
	v_rcp_f32_e32 v17, v13
	v_ashrrev_i32_e32 v13, 31, v12
	v_lshlrev_b64 v[8:9], 11, v[12:13]
	v_lshl_add_u64 v[8:9], v[0:1], 0, v[8:9]
	v_pk_mul_f32 v[14:15], v[16:17], v[14:15]
	s_nop 0
	v_pk_mul_f32 v[10:11], v[14:15], v[10:11]
	v_lshlrev_b32_e32 v14, 16, v104
	v_mul_f32_e32 v13, 0xbfb8aa3b, v14
	v_exp_f32_e32 v13, v13
	v_and_b32_e32 v15, 0xffff0000, v104
	v_cvt_pk_bf16_f32 v7, v10, v11
	global_store_dwordx4 v[8:9], v[4:7], off offset:1024
	v_add_f32_e32 v13, 1.0, v13
	v_rcp_f32_e32 v16, v13
	v_mul_f32_e32 v13, 0xbfb8aa3b, v15
	v_exp_f32_e32 v13, v13
	v_add_u32_e32 v4, 64, v2
	v_ashrrev_i32_e32 v12, 3, v4
	v_lshl_add_u32 v8, v12, 8, v3
	v_add_f32_e32 v13, 1.0, v13
	v_rcp_f32_e32 v17, v13
	ds_read_b128 v[4:7], v8
	ds_read_b128 v[8:11], v8 offset:16
	v_pk_mul_f32 v[14:15], v[16:17], v[14:15]
	s_waitcnt lgkmcnt(1)
	v_pk_mul_f32 v[4:5], v[14:15], v[4:5]
	v_lshlrev_b32_e32 v14, 16, v105
	v_mul_f32_e32 v13, 0xbfb8aa3b, v14
	v_exp_f32_e32 v13, v13
	v_and_b32_e32 v15, 0xffff0000, v105
	v_cvt_pk_bf16_f32 v4, v4, v5
	v_add_f32_e32 v13, 1.0, v13
	v_rcp_f32_e32 v16, v13
	v_mul_f32_e32 v13, 0xbfb8aa3b, v15
	v_exp_f32_e32 v13, v13
	s_nop 0
	v_add_f32_e32 v13, 1.0, v13
	v_rcp_f32_e32 v17, v13
	s_nop 0
	v_pk_mul_f32 v[14:15], v[16:17], v[14:15]
	s_nop 0
	v_pk_mul_f32 v[6:7], v[14:15], v[6:7]
	v_lshlrev_b32_e32 v14, 16, v106
	v_mul_f32_e32 v13, 0xbfb8aa3b, v14
	v_exp_f32_e32 v13, v13
	v_and_b32_e32 v15, 0xffff0000, v106
	v_cvt_pk_bf16_f32 v5, v6, v7
	v_add_f32_e32 v13, 1.0, v13
	v_rcp_f32_e32 v16, v13
	v_mul_f32_e32 v13, 0xbfb8aa3b, v15
	v_exp_f32_e32 v13, v13
	s_nop 0
	v_add_f32_e32 v13, 1.0, v13
	v_rcp_f32_e32 v17, v13
	s_nop 0
	v_pk_mul_f32 v[14:15], v[16:17], v[14:15]
	s_waitcnt lgkmcnt(0)
	v_pk_mul_f32 v[8:9], v[14:15], v[8:9]
	v_lshlrev_b32_e32 v14, 16, v107
	v_mul_f32_e32 v13, 0xbfb8aa3b, v14
	v_exp_f32_e32 v13, v13
	v_and_b32_e32 v15, 0xffff0000, v107
	v_cvt_pk_bf16_f32 v6, v8, v9
	v_add_f32_e32 v13, 1.0, v13
	v_rcp_f32_e32 v16, v13
	v_mul_f32_e32 v13, 0xbfb8aa3b, v15
	v_exp_f32_e32 v13, v13
	s_nop 0
	v_add_f32_e32 v13, 1.0, v13
	v_rcp_f32_e32 v17, v13
	v_ashrrev_i32_e32 v13, 31, v12
	v_lshlrev_b64 v[8:9], 11, v[12:13]
	v_lshl_add_u64 v[8:9], v[0:1], 0, v[8:9]
	v_pk_mul_f32 v[14:15], v[16:17], v[14:15]
	s_nop 0
	v_pk_mul_f32 v[10:11], v[14:15], v[10:11]
	v_lshlrev_b32_e32 v14, 16, v100
	v_mul_f32_e32 v13, 0xbfb8aa3b, v14
	v_exp_f32_e32 v13, v13
	v_and_b32_e32 v15, 0xffff0000, v100
	v_cvt_pk_bf16_f32 v7, v10, v11
	global_store_dwordx4 v[8:9], v[4:7], off offset:1024
	v_add_f32_e32 v13, 1.0, v13
	v_rcp_f32_e32 v16, v13
	v_mul_f32_e32 v13, 0xbfb8aa3b, v15
	v_exp_f32_e32 v13, v13
	v_add_u32_e32 v4, 0x80, v2
	v_ashrrev_i32_e32 v12, 3, v4
	v_lshl_add_u32 v8, v12, 8, v3
	v_add_f32_e32 v13, 1.0, v13
	v_rcp_f32_e32 v17, v13
	ds_read_b128 v[4:7], v8
	ds_read_b128 v[8:11], v8 offset:16
	v_add_u32_e32 v2, 0xc0, v2
	v_pk_mul_f32 v[14:15], v[16:17], v[14:15]
	s_waitcnt lgkmcnt(1)
	v_pk_mul_f32 v[4:5], v[14:15], v[4:5]
	v_lshlrev_b32_e32 v14, 16, v101
	v_mul_f32_e32 v13, 0xbfb8aa3b, v14
	v_exp_f32_e32 v13, v13
	v_and_b32_e32 v15, 0xffff0000, v101
	v_cvt_pk_bf16_f32 v4, v4, v5
	v_add_f32_e32 v13, 1.0, v13
	v_rcp_f32_e32 v16, v13
	v_mul_f32_e32 v13, 0xbfb8aa3b, v15
	v_exp_f32_e32 v13, v13
	s_nop 0
	v_add_f32_e32 v13, 1.0, v13
	v_rcp_f32_e32 v17, v13
	s_nop 0
	v_pk_mul_f32 v[14:15], v[16:17], v[14:15]
	s_nop 0
	v_pk_mul_f32 v[6:7], v[14:15], v[6:7]
	v_lshlrev_b32_e32 v14, 16, v102
	v_mul_f32_e32 v13, 0xbfb8aa3b, v14
	v_exp_f32_e32 v13, v13
	v_and_b32_e32 v15, 0xffff0000, v102
	v_cvt_pk_bf16_f32 v5, v6, v7
	v_add_f32_e32 v13, 1.0, v13
	v_rcp_f32_e32 v16, v13
	v_mul_f32_e32 v13, 0xbfb8aa3b, v15
	v_exp_f32_e32 v13, v13
	s_nop 0
	v_add_f32_e32 v13, 1.0, v13
	v_rcp_f32_e32 v17, v13
	s_nop 0
	v_pk_mul_f32 v[14:15], v[16:17], v[14:15]
	s_waitcnt lgkmcnt(0)
	v_pk_mul_f32 v[8:9], v[14:15], v[8:9]
	v_lshlrev_b32_e32 v14, 16, v103
	v_mul_f32_e32 v13, 0xbfb8aa3b, v14
	v_exp_f32_e32 v13, v13
	v_and_b32_e32 v15, 0xffff0000, v103
	v_cvt_pk_bf16_f32 v6, v8, v9
	v_add_f32_e32 v13, 1.0, v13
	v_rcp_f32_e32 v16, v13
	v_mul_f32_e32 v13, 0xbfb8aa3b, v15
	v_exp_f32_e32 v13, v13
	s_nop 0
	v_add_f32_e32 v13, 1.0, v13
	v_rcp_f32_e32 v17, v13
	v_ashrrev_i32_e32 v13, 31, v12
	v_lshlrev_b64 v[8:9], 11, v[12:13]
	v_lshlrev_b32_e32 v12, 16, v96
	v_pk_mul_f32 v[14:15], v[16:17], v[14:15]
	v_and_b32_e32 v13, 0xffff0000, v96
	v_pk_mul_f32 v[10:11], v[14:15], v[10:11]
	v_lshl_add_u64 v[8:9], v[0:1], 0, v[8:9]
	v_cvt_pk_bf16_f32 v7, v10, v11
	v_mul_f32_e32 v11, 0xbfb8aa3b, v12
	v_exp_f32_e32 v11, v11
	v_ashrrev_i32_e32 v10, 3, v2
	global_store_dwordx4 v[8:9], v[4:7], off offset:1024
	v_add_f32_e32 v11, 1.0, v11
	v_rcp_f32_e32 v14, v11
	v_mul_f32_e32 v11, 0xbfb8aa3b, v13
	v_exp_f32_e32 v11, v11
	v_lshl_add_u32 v6, v10, 8, v3
	ds_read_b128 v[2:5], v6
	ds_read_b128 v[6:9], v6 offset:16
	v_add_f32_e32 v11, 1.0, v11
	v_rcp_f32_e32 v15, v11
	s_nop 0
	v_pk_mul_f32 v[12:13], v[14:15], v[12:13]
	s_waitcnt lgkmcnt(1)
	v_pk_mul_f32 v[2:3], v[12:13], v[2:3]
	v_lshlrev_b32_e32 v12, 16, v97
	v_mul_f32_e32 v11, 0xbfb8aa3b, v12
	v_exp_f32_e32 v11, v11
	v_and_b32_e32 v13, 0xffff0000, v97
	v_cvt_pk_bf16_f32 v2, v2, v3
	v_add_f32_e32 v11, 1.0, v11
	v_rcp_f32_e32 v14, v11
	v_mul_f32_e32 v11, 0xbfb8aa3b, v13
	v_exp_f32_e32 v11, v11
	s_nop 0
	v_add_f32_e32 v11, 1.0, v11
	v_rcp_f32_e32 v15, v11
	s_nop 0
	v_pk_mul_f32 v[12:13], v[14:15], v[12:13]
	s_nop 0
	v_pk_mul_f32 v[4:5], v[12:13], v[4:5]
	v_lshlrev_b32_e32 v12, 16, v98
	v_mul_f32_e32 v11, 0xbfb8aa3b, v12
	v_exp_f32_e32 v11, v11
	v_and_b32_e32 v13, 0xffff0000, v98
	v_cvt_pk_bf16_f32 v3, v4, v5
	v_add_f32_e32 v11, 1.0, v11
	v_rcp_f32_e32 v14, v11
	v_mul_f32_e32 v11, 0xbfb8aa3b, v13
	v_exp_f32_e32 v11, v11
	s_nop 0
	v_add_f32_e32 v11, 1.0, v11
	v_rcp_f32_e32 v15, v11
	s_nop 0
	v_pk_mul_f32 v[12:13], v[14:15], v[12:13]
	s_waitcnt lgkmcnt(0)
	v_pk_mul_f32 v[6:7], v[12:13], v[6:7]
	v_lshlrev_b32_e32 v12, 16, v99
	v_mul_f32_e32 v11, 0xbfb8aa3b, v12
	v_exp_f32_e32 v11, v11
	v_and_b32_e32 v13, 0xffff0000, v99
	v_cvt_pk_bf16_f32 v4, v6, v7
	v_add_f32_e32 v11, 1.0, v11
	v_rcp_f32_e32 v14, v11
	v_mul_f32_e32 v11, 0xbfb8aa3b, v13
	v_exp_f32_e32 v11, v11
	s_nop 0
	v_add_f32_e32 v11, 1.0, v11
	v_rcp_f32_e32 v15, v11
	v_ashrrev_i32_e32 v11, 31, v10
	v_lshlrev_b64 v[6:7], 11, v[10:11]
	v_lshl_add_u64 v[0:1], v[0:1], 0, v[6:7]
	v_pk_mul_f32 v[12:13], v[14:15], v[12:13]
	s_nop 0
	v_pk_mul_f32 v[8:9], v[12:13], v[8:9]
	s_nop 0
	v_cvt_pk_bf16_f32 v5, v8, v9
	global_store_dwordx4 v[0:1], v[2:5], off offset:1024
	s_cbranch_vccz .LBB0_419
